# grid barrier: all waiters poll the cross-XCD arrival counter against (gen+1)*nx (no separate generation bump on the release path); per-XCD release add dropped
# baseline (speedup 1.0000x reference)
; __device__ __forceinline__ unsigned xb_ld(unsigned* p)              { return __hip_atomic_load(p, __ATOMIC_RELAXED, __HIP_MEMORY_SCOPE_AGENT); }
; __device__ __forceinline__ unsigned xb_add(unsigned* p, unsigned v) { return __hip_atomic_fetch_add(p, v, __ATOMIC_RELAXED, __HIP_MEMORY_SCOPE_AGENT); }
; #define XB_SPIN(cond, bar) do { unsigned _sp = 0; while (cond) { __builtin_amdgcn_s_sleep(1); \
;     if ((++_sp & 255u) == 0u) { if (xb_ld(&(bar)[XB_TMO])) break; if (_sp > XB_SPIN_CAP) { atomicAdd(&(bar)[XB_TMO], 1u); break; } } } } while (0)
; __device__ __forceinline__ void xcd_barrier(const XcdBarrier& b) {
;     ...
;         const unsigned old = xb_add(&bar[XB_XSUB(b.x)], 1u);
;         const unsigned gen = old / nloc;
;         if (old + 1u == (gen + 1u) * nloc) {
;             __builtin_amdgcn_fence(__ATOMIC_RELEASE, "agent");
;             asm volatile("s_waitcnt vmcnt(0)" ::: "memory");
;             const unsigned og = xb_add(&bar[XB_TOP], 1u);
;             const unsigned tg = og / nx;
;             if (og + 1u == (tg + 1u) * nx) xb_add(&bar[XB_TOPGEN], 1u);
;             else XB_SPIN(xb_ld(&bar[XB_TOPGEN]) == tg, bar);
;             __builtin_amdgcn_fence(__ATOMIC_ACQUIRE, "agent");
;             xb_add(&bar[XB_XGEN(b.x)], 1u);
;             asm volatile("s_waitcnt vmcnt(0)" ::: "memory");
;         } else {
;             XB_SPIN(xb_ld(&bar[XB_XGEN(b.x)]) == gen, bar);
;             __builtin_amdgcn_fence(__ATOMIC_ACQUIRE, "agent");
.LBB0_51:
	s_or_b64 exec, exec, s[6:7]
	v_cvt_f32_u32_e32 v5, v3
	s_waitcnt vmcnt(0)
	v_readfirstlane_b32 s2, v4
	v_sub_u32_e32 v4, 0, v3
	v_rcp_iflag_f32_e32 v5, v5
	v_add_u32_e32 v6, s2, v2
	v_mul_f32_e32 v5, 0x4f7ffffe, v5
	v_cvt_u32_f32_e32 v5, v5
	v_mul_lo_u32 v2, v4, v5
	v_mul_hi_u32 v2, v5, v2
	v_add_u32_e32 v2, v5, v2
	v_mul_hi_u32 v2, v6, v2
	v_mul_lo_u32 v4, v2, v3
	v_sub_u32_e32 v4, v6, v4
	v_add_u32_e32 v5, 1, v2
	v_cmp_ge_u32_e32 vcc, v4, v3
	s_nop 1
	v_cndmask_b32_e32 v2, v2, v5, vcc
	v_sub_u32_e32 v5, v4, v3
	v_cndmask_b32_e32 v4, v4, v5, vcc
	v_add_u32_e32 v5, 1, v2
	v_cmp_ge_u32_e32 vcc, v4, v3
	v_add_u32_e32 v4, 1, v6
	s_nop 0
	v_cndmask_b32_e32 v2, v2, v5, vcc
	v_mul_lo_u32 v5, v3, v2
	v_add_u32_e32 v3, v5, v3
	v_cmp_ne_u32_e32 vcc, v4, v3
	s_and_saveexec_b64 s[2:3], vcc
	s_xor_b64 s[2:3], exec, s[2:3]
	s_cbranch_execz .LBB0_65
	s_waitcnt lgkmcnt(0)
	v_mov_b32_e32 v255, 0x23f64
	ds_read_b32 v254, v255
	v_mov_b32_e32 v1, 0
	s_add_u32 s14, s54, 0x7400
	s_addc_u32 s15, s55, 0
	global_load_dword v1, v1, s[14:15] sc1
	s_waitcnt lgkmcnt(0)
	v_mad_u32_u24 v254, v2, v254, v254
	s_waitcnt vmcnt(0)
	v_cmp_lt_u32_e32 vcc, v1, v254
	s_and_saveexec_b64 s[6:7], vcc
	s_cbranch_execz .LBB0_64
	s_add_u32 s12, s54, 0x4200
	s_addc_u32 s13, s55, 0
	s_mov_b32 s26, 1
	s_mov_b64 s[16:17], 0
	v_mov_b32_e32 v1, 0
	s_branch .LBB0_55

; __device__ __forceinline__ unsigned xb_ld(unsigned* p)              { return __hip_atomic_load(p, __ATOMIC_RELAXED, __HIP_MEMORY_SCOPE_AGENT); }
; #define XB_SPIN(cond, bar) do { unsigned _sp = 0; while (cond) { __builtin_amdgcn_s_sleep(1); \
;     if ((++_sp & 255u) == 0u) { if (xb_ld(&(bar)[XB_TMO])) break; if (_sp > XB_SPIN_CAP) { atomicAdd(&(bar)[XB_TMO], 1u); break; } } } } while (0)
; __device__ __forceinline__ void xcd_barrier(const XcdBarrier& b) {
;     ...
;             XB_SPIN(xb_ld(&bar[XB_XGEN(b.x)]) == gen, bar);
.LBB0_59:
	global_load_dword v3, v1, s[14:15] sc1
	s_add_i32 s26, s26, 1
	s_mov_b64 s[22:23], -1
	s_waitcnt vmcnt(0)
	v_cmp_ge_u32_e32 vcc, v3, v254
	s_orn2_b64 s[20:21], vcc, exec
	s_branch .LBB0_54

; __device__ __forceinline__ unsigned xb_ld(unsigned* p)              { return __hip_atomic_load(p, __ATOMIC_RELAXED, __HIP_MEMORY_SCOPE_AGENT); }
; __device__ __forceinline__ unsigned xb_add(unsigned* p, unsigned v) { return __hip_atomic_fetch_add(p, v, __ATOMIC_RELAXED, __HIP_MEMORY_SCOPE_AGENT); }
; #define XB_SPIN(cond, bar) do { unsigned _sp = 0; while (cond) { __builtin_amdgcn_s_sleep(1); \
;     if ((++_sp & 255u) == 0u) { if (xb_ld(&(bar)[XB_TMO])) break; if (_sp > XB_SPIN_CAP) { atomicAdd(&(bar)[XB_TMO], 1u); break; } } } } while (0)
; __device__ __forceinline__ void xcd_barrier(const XcdBarrier& b) {
;     ...
;         if (old + 1u == (gen + 1u) * nloc) {
;             __builtin_amdgcn_fence(__ATOMIC_RELEASE, "agent");
;             asm volatile("s_waitcnt vmcnt(0)" ::: "memory");
;             const unsigned og = xb_add(&bar[XB_TOP], 1u);
;             const unsigned tg = og / nx;
;             if (og + 1u == (tg + 1u) * nx) xb_add(&bar[XB_TOPGEN], 1u);
;             else XB_SPIN(xb_ld(&bar[XB_TOPGEN]) == tg, bar);
.LBB0_68:
	s_or_b64 exec, exec, s[6:7]
	v_cvt_f32_u32_e32 v4, v1
	s_waitcnt vmcnt(0)
	v_readfirstlane_b32 s2, v3
	s_add_u32 s6, s54, 0x7500
	s_addc_u32 s7, s55, 0
	v_rcp_iflag_f32_e32 v4, v4
	v_add_u32_e32 v2, s2, v2
	v_add_u32_e32 v5, 1, v2
	s_mov_b64 s[12:13], -1
	v_mul_f32_e32 v3, 0x4f7ffffe, v4
	v_cvt_u32_f32_e32 v3, v3
	v_sub_u32_e32 v4, 0, v1
	v_mul_lo_u32 v4, v4, v3
	v_mul_hi_u32 v4, v3, v4
	v_add_u32_e32 v3, v3, v4
	v_mul_hi_u32 v3, v2, v3
	v_mul_lo_u32 v4, v3, v1
	v_sub_u32_e32 v2, v2, v4
	v_add_u32_e32 v6, 1, v3
	v_cmp_ge_u32_e32 vcc, v2, v1
	v_sub_u32_e32 v4, v2, v1
	s_nop 0
	v_cndmask_b32_e32 v3, v3, v6, vcc
	v_cndmask_b32_e32 v2, v2, v4, vcc
	v_add_u32_e32 v4, 1, v3
	v_cmp_ge_u32_e32 vcc, v2, v1
	s_nop 1
	v_cndmask_b32_e32 v4, v3, v4, vcc
	v_mul_lo_u32 v2, v1, v4
	v_add_u32_e32 v1, v2, v1
	v_mov_b32_e32 v253, v1
	v_cmp_ne_u32_e32 vcc, v5, v1
	v_mov_b64_e32 v[2:3], s[6:7]
	s_and_saveexec_b64 s[2:3], vcc
	s_cbranch_execz .LBB0_80
	v_mov_b32_e32 v1, 0
	global_load_dword v2, v1, s[6:7] offset:-256 sc1
	s_mov_b64 s[16:17], 0
	s_waitcnt vmcnt(0)
	v_cmp_lt_u32_e32 vcc, v2, v253
	s_and_saveexec_b64 s[14:15], vcc
	s_cbranch_execz .LBB0_79
	s_add_u32 s12, s54, 0x4200
	s_addc_u32 s13, s55, 0
	s_mov_b32 s26, 1
	s_branch .LBB0_72

; __device__ __forceinline__ unsigned xb_ld(unsigned* p)              { return __hip_atomic_load(p, __ATOMIC_RELAXED, __HIP_MEMORY_SCOPE_AGENT); }
; #define XB_SPIN(cond, bar) do { unsigned _sp = 0; while (cond) { __builtin_amdgcn_s_sleep(1); \
;     if ((++_sp & 255u) == 0u) { if (xb_ld(&(bar)[XB_TMO])) break; if (_sp > XB_SPIN_CAP) { atomicAdd(&(bar)[XB_TMO], 1u); break; } } } } while (0)
; __device__ __forceinline__ void xcd_barrier(const XcdBarrier& b) {
;     ...
;             else XB_SPIN(xb_ld(&bar[XB_TOPGEN]) == tg, bar);
.LBB0_76:
	global_load_dword v2, v1, s[6:7] offset:-256 sc1
	s_add_i32 s26, s26, 1
	s_mov_b64 s[20:21], -1
	s_waitcnt vmcnt(0)
	v_cmp_ge_u32_e32 vcc, v2, v253
	s_orn2_b64 s[24:25], vcc, exec
	s_branch .LBB0_71

; __device__ __forceinline__ unsigned xb_add(unsigned* p, unsigned v) { return __hip_atomic_fetch_add(p, v, __ATOMIC_RELAXED, __HIP_MEMORY_SCOPE_AGENT); }
; __device__ __forceinline__ void xcd_barrier(const XcdBarrier& b) {
;     ...
;             __builtin_amdgcn_fence(__ATOMIC_ACQUIRE, "agent");
;             xb_add(&bar[XB_XGEN(b.x)], 1u);
;             asm volatile("s_waitcnt vmcnt(0)" ::: "memory");
.LBB0_82:
	s_or_b64 exec, exec, s[2:3]
	s_mov_b64 s[2:3], exec
	v_mbcnt_lo_u32_b32 v1, s2, 0
	v_mbcnt_hi_u32_b32 v1, s3, v1
	v_cmp_eq_u32_e32 vcc, 0, v1
	s_waitcnt vmcnt(0)
	buffer_inv sc1
	s_and_saveexec_b64 s[6:7], vcc
	s_cbranch_execz .LBB0_84
	s_bcnt1_i32_b64 s2, s[2:3]
	v_mov_b32_e32 v1, 0x2000
	v_mov_b32_e32 v2, s2
	s_nop 0

; __device__ __forceinline__ unsigned xb_ld(unsigned* p)              { return __hip_atomic_load(p, __ATOMIC_RELAXED, __HIP_MEMORY_SCOPE_AGENT); }
; __device__ __forceinline__ unsigned xb_add(unsigned* p, unsigned v) { return __hip_atomic_fetch_add(p, v, __ATOMIC_RELAXED, __HIP_MEMORY_SCOPE_AGENT); }
; #define XB_SPIN(cond, bar) do { unsigned _sp = 0; while (cond) { __builtin_amdgcn_s_sleep(1); \
;     if ((++_sp & 255u) == 0u) { if (xb_ld(&(bar)[XB_TMO])) break; if (_sp > XB_SPIN_CAP) { atomicAdd(&(bar)[XB_TMO], 1u); break; } } } } while (0)
; __device__ __forceinline__ void xcd_barrier(const XcdBarrier& b) {
;     ...
;         const unsigned old = xb_add(&bar[XB_XSUB(b.x)], 1u);
;         const unsigned gen = old / nloc;
;         if (old + 1u == (gen + 1u) * nloc) {
;             __builtin_amdgcn_fence(__ATOMIC_RELEASE, "agent");
;             asm volatile("s_waitcnt vmcnt(0)" ::: "memory");
;             const unsigned og = xb_add(&bar[XB_TOP], 1u);
;             const unsigned tg = og / nx;
;             if (og + 1u == (tg + 1u) * nx) xb_add(&bar[XB_TOPGEN], 1u);
;             else XB_SPIN(xb_ld(&bar[XB_TOPGEN]) == tg, bar);
;             __builtin_amdgcn_fence(__ATOMIC_ACQUIRE, "agent");
;             xb_add(&bar[XB_XGEN(b.x)], 1u);
;             asm volatile("s_waitcnt vmcnt(0)" ::: "memory");
;         } else {
;             XB_SPIN(xb_ld(&bar[XB_XGEN(b.x)]) == gen, bar);
;             __builtin_amdgcn_fence(__ATOMIC_ACQUIRE, "agent");
.LBB0_134:
	s_or_b64 exec, exec, s[6:7]
	v_cvt_f32_u32_e32 v5, v3
	s_waitcnt vmcnt(0)
	v_readfirstlane_b32 s2, v4
	v_sub_u32_e32 v4, 0, v3
	v_rcp_iflag_f32_e32 v5, v5
	v_add_u32_e32 v6, s2, v2
	v_mul_f32_e32 v5, 0x4f7ffffe, v5
	v_cvt_u32_f32_e32 v5, v5
	v_mul_lo_u32 v2, v4, v5
	v_mul_hi_u32 v2, v5, v2
	v_add_u32_e32 v2, v5, v2
	v_mul_hi_u32 v2, v6, v2
	v_mul_lo_u32 v4, v2, v3
	v_sub_u32_e32 v4, v6, v4
	v_add_u32_e32 v5, 1, v2
	v_cmp_ge_u32_e32 vcc, v4, v3
	s_nop 1
	v_cndmask_b32_e32 v2, v2, v5, vcc
	v_sub_u32_e32 v5, v4, v3
	v_cndmask_b32_e32 v4, v4, v5, vcc
	v_add_u32_e32 v5, 1, v2
	v_cmp_ge_u32_e32 vcc, v4, v3
	v_add_u32_e32 v4, 1, v6
	s_nop 0
	v_cndmask_b32_e32 v2, v2, v5, vcc
	v_mul_lo_u32 v5, v3, v2
	v_add_u32_e32 v3, v5, v3
	v_cmp_ne_u32_e32 vcc, v4, v3
	s_and_saveexec_b64 s[2:3], vcc
	s_xor_b64 s[2:3], exec, s[2:3]
	s_cbranch_execz .LBB0_148
	s_waitcnt lgkmcnt(0)
	v_mov_b32_e32 v255, 0x23f64
	ds_read_b32 v254, v255
	v_mov_b32_e32 v1, 0
	s_add_u32 s12, s54, 0x7400
	s_addc_u32 s13, s55, 0
	global_load_dword v1, v1, s[12:13] sc1
	s_waitcnt lgkmcnt(0)
	v_mad_u32_u24 v254, v2, v254, v254
	s_waitcnt vmcnt(0)
	v_cmp_lt_u32_e32 vcc, v1, v254
	s_and_saveexec_b64 s[6:7], vcc
	s_cbranch_execz .LBB0_147
	s_add_u32 s10, s54, 0x4200
	s_addc_u32 s11, s55, 0
	s_mov_b32 s26, 1
	s_mov_b64 s[14:15], 0
	v_mov_b32_e32 v1, 0
	s_branch .LBB0_138

; __device__ __forceinline__ unsigned xb_ld(unsigned* p)              { return __hip_atomic_load(p, __ATOMIC_RELAXED, __HIP_MEMORY_SCOPE_AGENT); }
; #define XB_SPIN(cond, bar) do { unsigned _sp = 0; while (cond) { __builtin_amdgcn_s_sleep(1); \
;     if ((++_sp & 255u) == 0u) { if (xb_ld(&(bar)[XB_TMO])) break; if (_sp > XB_SPIN_CAP) { atomicAdd(&(bar)[XB_TMO], 1u); break; } } } } while (0)
; __device__ __forceinline__ void xcd_barrier(const XcdBarrier& b) {
;     ...
;             XB_SPIN(xb_ld(&bar[XB_XGEN(b.x)]) == gen, bar);
.LBB0_142:
	global_load_dword v3, v1, s[12:13] sc1
	s_add_i32 s26, s26, 1
	s_mov_b64 s[22:23], -1
	s_waitcnt vmcnt(0)
	v_cmp_ge_u32_e32 vcc, v3, v254
	s_orn2_b64 s[20:21], vcc, exec
	s_branch .LBB0_137

; __device__ __forceinline__ unsigned xb_ld(unsigned* p)              { return __hip_atomic_load(p, __ATOMIC_RELAXED, __HIP_MEMORY_SCOPE_AGENT); }
; __device__ __forceinline__ unsigned xb_add(unsigned* p, unsigned v) { return __hip_atomic_fetch_add(p, v, __ATOMIC_RELAXED, __HIP_MEMORY_SCOPE_AGENT); }
; #define XB_SPIN(cond, bar) do { unsigned _sp = 0; while (cond) { __builtin_amdgcn_s_sleep(1); \
;     if ((++_sp & 255u) == 0u) { if (xb_ld(&(bar)[XB_TMO])) break; if (_sp > XB_SPIN_CAP) { atomicAdd(&(bar)[XB_TMO], 1u); break; } } } } while (0)
; __device__ __forceinline__ void xcd_barrier(const XcdBarrier& b) {
;     ...
;         if (old + 1u == (gen + 1u) * nloc) {
;             __builtin_amdgcn_fence(__ATOMIC_RELEASE, "agent");
;             asm volatile("s_waitcnt vmcnt(0)" ::: "memory");
;             const unsigned og = xb_add(&bar[XB_TOP], 1u);
;             const unsigned tg = og / nx;
;             if (og + 1u == (tg + 1u) * nx) xb_add(&bar[XB_TOPGEN], 1u);
;             else XB_SPIN(xb_ld(&bar[XB_TOPGEN]) == tg, bar);
.LBB0_151:
	s_or_b64 exec, exec, s[6:7]
	v_cvt_f32_u32_e32 v4, v1
	s_waitcnt vmcnt(0)
	v_readfirstlane_b32 s2, v3
	s_add_u32 s6, s54, 0x7500
	s_addc_u32 s7, s55, 0
	v_rcp_iflag_f32_e32 v4, v4
	v_add_u32_e32 v2, s2, v2
	v_add_u32_e32 v5, 1, v2
	s_mov_b64 s[10:11], -1
	v_mul_f32_e32 v3, 0x4f7ffffe, v4
	v_cvt_u32_f32_e32 v3, v3
	v_sub_u32_e32 v4, 0, v1
	v_mul_lo_u32 v4, v4, v3
	v_mul_hi_u32 v4, v3, v4
	v_add_u32_e32 v3, v3, v4
	v_mul_hi_u32 v3, v2, v3
	v_mul_lo_u32 v4, v3, v1
	v_sub_u32_e32 v2, v2, v4
	v_add_u32_e32 v6, 1, v3
	v_cmp_ge_u32_e32 vcc, v2, v1
	v_sub_u32_e32 v4, v2, v1
	s_nop 0
	v_cndmask_b32_e32 v3, v3, v6, vcc
	v_cndmask_b32_e32 v2, v2, v4, vcc
	v_add_u32_e32 v4, 1, v3
	v_cmp_ge_u32_e32 vcc, v2, v1
	s_nop 1
	v_cndmask_b32_e32 v4, v3, v4, vcc
	v_mul_lo_u32 v2, v1, v4
	v_add_u32_e32 v1, v2, v1
	v_mov_b32_e32 v253, v1
	v_cmp_ne_u32_e32 vcc, v5, v1
	v_mov_b64_e32 v[2:3], s[6:7]
	s_and_saveexec_b64 s[2:3], vcc
	s_cbranch_execz .LBB0_163
	v_mov_b32_e32 v1, 0
	global_load_dword v2, v1, s[6:7] offset:-256 sc1
	s_mov_b64 s[14:15], 0
	s_waitcnt vmcnt(0)
	v_cmp_lt_u32_e32 vcc, v2, v253
	s_and_saveexec_b64 s[12:13], vcc
	s_cbranch_execz .LBB0_162
	s_add_u32 s10, s54, 0x4200
	s_addc_u32 s11, s55, 0
	s_mov_b32 s26, 1
	s_branch .LBB0_155

; __device__ __forceinline__ unsigned xb_ld(unsigned* p)              { return __hip_atomic_load(p, __ATOMIC_RELAXED, __HIP_MEMORY_SCOPE_AGENT); }
; __device__ __forceinline__ unsigned xb_add(unsigned* p, unsigned v) { return __hip_atomic_fetch_add(p, v, __ATOMIC_RELAXED, __HIP_MEMORY_SCOPE_AGENT); }
; #define XB_SPIN(cond, bar) do { unsigned _sp = 0; while (cond) { __builtin_amdgcn_s_sleep(1); \
;     if ((++_sp & 255u) == 0u) { if (xb_ld(&(bar)[XB_TMO])) break; if (_sp > XB_SPIN_CAP) { atomicAdd(&(bar)[XB_TMO], 1u); break; } } } } while (0)
; __device__ __forceinline__ void xcd_barrier(const XcdBarrier& b) {
;     ...
;         const unsigned old = xb_add(&bar[XB_XSUB(b.x)], 1u);
;         const unsigned gen = old / nloc;
;         if (old + 1u == (gen + 1u) * nloc) {
;             __builtin_amdgcn_fence(__ATOMIC_RELEASE, "agent");
;             asm volatile("s_waitcnt vmcnt(0)" ::: "memory");
;             const unsigned og = xb_add(&bar[XB_TOP], 1u);
;             const unsigned tg = og / nx;
;             if (og + 1u == (tg + 1u) * nx) xb_add(&bar[XB_TOPGEN], 1u);
;             else XB_SPIN(xb_ld(&bar[XB_TOPGEN]) == tg, bar);
;             __builtin_amdgcn_fence(__ATOMIC_ACQUIRE, "agent");
;             xb_add(&bar[XB_XGEN(b.x)], 1u);
;             asm volatile("s_waitcnt vmcnt(0)" ::: "memory");
;         } else {
;             XB_SPIN(xb_ld(&bar[XB_XGEN(b.x)]) == gen, bar);
;             __builtin_amdgcn_fence(__ATOMIC_ACQUIRE, "agent");
.LBB0_281:
	s_or_b64 exec, exec, s[6:7]
	v_cvt_f32_u32_e32 v5, v3
	s_waitcnt vmcnt(0)
	v_readfirstlane_b32 s2, v4
	v_sub_u32_e32 v4, 0, v3
	v_rcp_iflag_f32_e32 v5, v5
	v_add_u32_e32 v6, s2, v2
	v_mul_f32_e32 v5, 0x4f7ffffe, v5
	v_cvt_u32_f32_e32 v5, v5
	v_mul_lo_u32 v2, v4, v5
	v_mul_hi_u32 v2, v5, v2
	v_add_u32_e32 v2, v5, v2
	v_mul_hi_u32 v2, v6, v2
	v_mul_lo_u32 v4, v2, v3
	v_sub_u32_e32 v4, v6, v4
	v_add_u32_e32 v5, 1, v2
	v_cmp_ge_u32_e32 vcc, v4, v3
	s_nop 1
	v_cndmask_b32_e32 v2, v2, v5, vcc
	v_sub_u32_e32 v5, v4, v3
	v_cndmask_b32_e32 v4, v4, v5, vcc
	v_add_u32_e32 v5, 1, v2
	v_cmp_ge_u32_e32 vcc, v4, v3
	v_add_u32_e32 v4, 1, v6
	s_nop 0
	v_cndmask_b32_e32 v2, v2, v5, vcc
	v_mul_lo_u32 v5, v3, v2
	v_add_u32_e32 v3, v5, v3
	v_cmp_ne_u32_e32 vcc, v4, v3
	s_and_saveexec_b64 s[2:3], vcc
	s_xor_b64 s[2:3], exec, s[2:3]
	s_cbranch_execz .LBB0_295
	s_waitcnt lgkmcnt(0)
	v_mov_b32_e32 v255, 0x23f64
	ds_read_b32 v254, v255
	v_mov_b32_e32 v1, 0
	s_add_u32 s10, s54, 0x7400
	s_addc_u32 s11, s55, 0
	global_load_dword v1, v1, s[10:11] sc1
	s_waitcnt lgkmcnt(0)
	v_mad_u32_u24 v254, v2, v254, v254
	s_waitcnt vmcnt(0)
	v_cmp_lt_u32_e32 vcc, v1, v254
	s_and_saveexec_b64 s[6:7], vcc
	s_cbranch_execz .LBB0_294
	s_add_u32 s8, s54, 0x4200
	s_addc_u32 s9, s55, 0
	s_mov_b32 s24, 1
	s_mov_b64 s[12:13], 0
	v_mov_b32_e32 v1, 0
	s_branch .LBB0_285

; __device__ __forceinline__ unsigned xb_ld(unsigned* p)              { return __hip_atomic_load(p, __ATOMIC_RELAXED, __HIP_MEMORY_SCOPE_AGENT); }
; #define XB_SPIN(cond, bar) do { unsigned _sp = 0; while (cond) { __builtin_amdgcn_s_sleep(1); \
;     if ((++_sp & 255u) == 0u) { if (xb_ld(&(bar)[XB_TMO])) break; if (_sp > XB_SPIN_CAP) { atomicAdd(&(bar)[XB_TMO], 1u); break; } } } } while (0)
; __device__ __forceinline__ void xcd_barrier(const XcdBarrier& b) {
;     ...
;             XB_SPIN(xb_ld(&bar[XB_XGEN(b.x)]) == gen, bar);
.LBB0_289:
	global_load_dword v3, v1, s[10:11] sc1
	s_add_i32 s24, s24, 1
	s_mov_b64 s[20:21], -1
	s_waitcnt vmcnt(0)
	v_cmp_ge_u32_e32 vcc, v3, v254
	s_orn2_b64 s[16:17], vcc, exec
	s_branch .LBB0_284

; __device__ __forceinline__ unsigned xb_ld(unsigned* p)              { return __hip_atomic_load(p, __ATOMIC_RELAXED, __HIP_MEMORY_SCOPE_AGENT); }
; __device__ __forceinline__ unsigned xb_add(unsigned* p, unsigned v) { return __hip_atomic_fetch_add(p, v, __ATOMIC_RELAXED, __HIP_MEMORY_SCOPE_AGENT); }
; #define XB_SPIN(cond, bar) do { unsigned _sp = 0; while (cond) { __builtin_amdgcn_s_sleep(1); \
;     if ((++_sp & 255u) == 0u) { if (xb_ld(&(bar)[XB_TMO])) break; if (_sp > XB_SPIN_CAP) { atomicAdd(&(bar)[XB_TMO], 1u); break; } } } } while (0)
; __device__ __forceinline__ void xcd_barrier(const XcdBarrier& b) {
;     ...
;         if (old + 1u == (gen + 1u) * nloc) {
;             __builtin_amdgcn_fence(__ATOMIC_RELEASE, "agent");
;             asm volatile("s_waitcnt vmcnt(0)" ::: "memory");
;             const unsigned og = xb_add(&bar[XB_TOP], 1u);
;             const unsigned tg = og / nx;
;             if (og + 1u == (tg + 1u) * nx) xb_add(&bar[XB_TOPGEN], 1u);
;             else XB_SPIN(xb_ld(&bar[XB_TOPGEN]) == tg, bar);
.LBB0_298:
	s_or_b64 exec, exec, s[6:7]
	v_cvt_f32_u32_e32 v4, v1
	s_waitcnt vmcnt(0)
	v_readfirstlane_b32 s2, v3
	s_add_u32 s6, s54, 0x7500
	s_addc_u32 s7, s55, 0
	v_rcp_iflag_f32_e32 v4, v4
	v_add_u32_e32 v2, s2, v2
	v_add_u32_e32 v5, 1, v2
	s_mov_b64 s[8:9], -1
	v_mul_f32_e32 v3, 0x4f7ffffe, v4
	v_cvt_u32_f32_e32 v3, v3
	v_sub_u32_e32 v4, 0, v1
	v_mul_lo_u32 v4, v4, v3
	v_mul_hi_u32 v4, v3, v4
	v_add_u32_e32 v3, v3, v4
	v_mul_hi_u32 v3, v2, v3
	v_mul_lo_u32 v4, v3, v1
	v_sub_u32_e32 v2, v2, v4
	v_add_u32_e32 v6, 1, v3
	v_cmp_ge_u32_e32 vcc, v2, v1
	v_sub_u32_e32 v4, v2, v1
	s_nop 0
	v_cndmask_b32_e32 v3, v3, v6, vcc
	v_cndmask_b32_e32 v2, v2, v4, vcc
	v_add_u32_e32 v4, 1, v3
	v_cmp_ge_u32_e32 vcc, v2, v1
	s_nop 1
	v_cndmask_b32_e32 v4, v3, v4, vcc
	v_mul_lo_u32 v2, v1, v4
	v_add_u32_e32 v1, v2, v1
	v_mov_b32_e32 v253, v1
	v_cmp_ne_u32_e32 vcc, v5, v1
	v_mov_b64_e32 v[2:3], s[6:7]
	s_and_saveexec_b64 s[2:3], vcc
	s_cbranch_execz .LBB0_310
	v_mov_b32_e32 v1, 0
	global_load_dword v2, v1, s[6:7] offset:-256 sc1
	s_mov_b64 s[12:13], 0
	s_waitcnt vmcnt(0)
	v_cmp_lt_u32_e32 vcc, v2, v253
	s_and_saveexec_b64 s[10:11], vcc
	s_cbranch_execz .LBB0_309
	s_add_u32 s8, s54, 0x4200
	s_addc_u32 s9, s55, 0
	s_mov_b32 s24, 1
	s_branch .LBB0_302

; __device__ __forceinline__ unsigned xb_ld(unsigned* p)              { return __hip_atomic_load(p, __ATOMIC_RELAXED, __HIP_MEMORY_SCOPE_AGENT); }
; #define XB_SPIN(cond, bar) do { unsigned _sp = 0; while (cond) { __builtin_amdgcn_s_sleep(1); \
;     if ((++_sp & 255u) == 0u) { if (xb_ld(&(bar)[XB_TMO])) break; if (_sp > XB_SPIN_CAP) { atomicAdd(&(bar)[XB_TMO], 1u); break; } } } } while (0)
; __device__ __forceinline__ void xcd_barrier(const XcdBarrier& b) {
;     ...
;             else XB_SPIN(xb_ld(&bar[XB_TOPGEN]) == tg, bar);
.LBB0_306:
	global_load_dword v2, v1, s[6:7] offset:-256 sc1
	s_add_i32 s24, s24, 1
	s_mov_b64 s[16:17], -1
	s_waitcnt vmcnt(0)
	v_cmp_ge_u32_e32 vcc, v2, v253
	s_orn2_b64 s[22:23], vcc, exec
	s_branch .LBB0_301

; __device__ __forceinline__ unsigned xb_ld(unsigned* p)              { return __hip_atomic_load(p, __ATOMIC_RELAXED, __HIP_MEMORY_SCOPE_AGENT); }
; __device__ __forceinline__ unsigned xb_add(unsigned* p, unsigned v) { return __hip_atomic_fetch_add(p, v, __ATOMIC_RELAXED, __HIP_MEMORY_SCOPE_AGENT); }
; #define XB_SPIN(cond, bar) do { unsigned _sp = 0; while (cond) { __builtin_amdgcn_s_sleep(1); \
;     if ((++_sp & 255u) == 0u) { if (xb_ld(&(bar)[XB_TMO])) break; if (_sp > XB_SPIN_CAP) { atomicAdd(&(bar)[XB_TMO], 1u); break; } } } } while (0)
; __device__ __forceinline__ void xcd_barrier(const XcdBarrier& b) {
;     ...
;         const unsigned old = xb_add(&bar[XB_XSUB(b.x)], 1u);
;         const unsigned gen = old / nloc;
;         if (old + 1u == (gen + 1u) * nloc) {
;             __builtin_amdgcn_fence(__ATOMIC_RELEASE, "agent");
;             asm volatile("s_waitcnt vmcnt(0)" ::: "memory");
;             const unsigned og = xb_add(&bar[XB_TOP], 1u);
;             const unsigned tg = og / nx;
;             if (og + 1u == (tg + 1u) * nx) xb_add(&bar[XB_TOPGEN], 1u);
;             else XB_SPIN(xb_ld(&bar[XB_TOPGEN]) == tg, bar);
;             __builtin_amdgcn_fence(__ATOMIC_ACQUIRE, "agent");
;             xb_add(&bar[XB_XGEN(b.x)], 1u);
;             asm volatile("s_waitcnt vmcnt(0)" ::: "memory");
;         } else {
;             XB_SPIN(xb_ld(&bar[XB_XGEN(b.x)]) == gen, bar);
;             __builtin_amdgcn_fence(__ATOMIC_ACQUIRE, "agent");
.LBB0_971:
	s_or_b64 exec, exec, s[6:7]
	v_cvt_f32_u32_e32 v5, v3
	s_waitcnt vmcnt(0)
	v_readfirstlane_b32 s2, v4
	v_sub_u32_e32 v4, 0, v3
	v_rcp_iflag_f32_e32 v5, v5
	v_add_u32_e32 v6, s2, v2
	v_mul_f32_e32 v5, 0x4f7ffffe, v5
	v_cvt_u32_f32_e32 v5, v5
	v_mul_lo_u32 v2, v4, v5
	v_mul_hi_u32 v2, v5, v2
	v_add_u32_e32 v2, v5, v2
	v_mul_hi_u32 v2, v6, v2
	v_mul_lo_u32 v4, v2, v3
	v_sub_u32_e32 v4, v6, v4
	v_add_u32_e32 v5, 1, v2
	v_cmp_ge_u32_e32 vcc, v4, v3
	s_nop 1
	v_cndmask_b32_e32 v2, v2, v5, vcc
	v_sub_u32_e32 v5, v4, v3
	v_cndmask_b32_e32 v4, v4, v5, vcc
	v_add_u32_e32 v5, 1, v2
	v_cmp_ge_u32_e32 vcc, v4, v3
	v_add_u32_e32 v4, 1, v6
	s_nop 0
	v_cndmask_b32_e32 v2, v2, v5, vcc
	v_mul_lo_u32 v5, v3, v2
	v_add_u32_e32 v3, v5, v3
	v_cmp_ne_u32_e32 vcc, v4, v3
	s_and_saveexec_b64 s[2:3], vcc
	s_xor_b64 s[2:3], exec, s[2:3]
	s_cbranch_execz .LBB0_985
	s_waitcnt lgkmcnt(0)
	v_mov_b32_e32 v255, 0x23f64
	ds_read_b32 v254, v255
	v_mov_b32_e32 v1, 0
	v_readlane_b32 s10, v244, 24
	v_readlane_b32 s11, v244, 25
	s_nop 1
	s_add_u32 s10, s10, 0x7400
	s_addc_u32 s11, s11, 0
	global_load_dword v1, v1, s[10:11] sc1
	s_waitcnt lgkmcnt(0)
	v_mad_u32_u24 v254, v2, v254, v254
	s_waitcnt vmcnt(0)
	v_cmp_lt_u32_e32 vcc, v1, v254
	s_and_saveexec_b64 s[6:7], vcc
	s_cbranch_execz .LBB0_984
	v_readlane_b32 s8, v244, 24
	v_readlane_b32 s9, v244, 25
	s_add_u32 s8, s8, 0x4200
	s_addc_u32 s9, s9, 0
	s_mov_b32 s22, 1
	s_mov_b64 s[12:13], 0
	v_mov_b32_e32 v1, 0
	s_branch .LBB0_975

; __device__ __forceinline__ unsigned xb_ld(unsigned* p)              { return __hip_atomic_load(p, __ATOMIC_RELAXED, __HIP_MEMORY_SCOPE_AGENT); }
; #define XB_SPIN(cond, bar) do { unsigned _sp = 0; while (cond) { __builtin_amdgcn_s_sleep(1); \
;     if ((++_sp & 255u) == 0u) { if (xb_ld(&(bar)[XB_TMO])) break; if (_sp > XB_SPIN_CAP) { atomicAdd(&(bar)[XB_TMO], 1u); break; } } } } while (0)
; __device__ __forceinline__ void xcd_barrier(const XcdBarrier& b) {
;     ...
;             XB_SPIN(xb_ld(&bar[XB_XGEN(b.x)]) == gen, bar);
.LBB0_979:
	global_load_dword v3, v1, s[10:11] sc1
	s_add_i32 s22, s22, 1
	s_mov_b64 s[18:19], -1
	s_waitcnt vmcnt(0)
	v_cmp_ge_u32_e32 vcc, v3, v254
	s_orn2_b64 s[16:17], vcc, exec
	s_branch .LBB0_974

; __device__ __forceinline__ unsigned xb_ld(unsigned* p)              { return __hip_atomic_load(p, __ATOMIC_RELAXED, __HIP_MEMORY_SCOPE_AGENT); }
; __device__ __forceinline__ unsigned xb_add(unsigned* p, unsigned v) { return __hip_atomic_fetch_add(p, v, __ATOMIC_RELAXED, __HIP_MEMORY_SCOPE_AGENT); }
; #define XB_SPIN(cond, bar) do { unsigned _sp = 0; while (cond) { __builtin_amdgcn_s_sleep(1); \
;     if ((++_sp & 255u) == 0u) { if (xb_ld(&(bar)[XB_TMO])) break; if (_sp > XB_SPIN_CAP) { atomicAdd(&(bar)[XB_TMO], 1u); break; } } } } while (0)
; __device__ __forceinline__ void xcd_barrier(const XcdBarrier& b) {
;     ...
;         if (old + 1u == (gen + 1u) * nloc) {
;             __builtin_amdgcn_fence(__ATOMIC_RELEASE, "agent");
;             asm volatile("s_waitcnt vmcnt(0)" ::: "memory");
;             const unsigned og = xb_add(&bar[XB_TOP], 1u);
;             const unsigned tg = og / nx;
;             if (og + 1u == (tg + 1u) * nx) xb_add(&bar[XB_TOPGEN], 1u);
;             else XB_SPIN(xb_ld(&bar[XB_TOPGEN]) == tg, bar);
.LBB0_988:
	s_or_b64 exec, exec, s[6:7]
	v_cvt_f32_u32_e32 v4, v1
	s_waitcnt vmcnt(0)
	v_readfirstlane_b32 s2, v3
	s_mov_b64 s[8:9], -1
	v_rcp_iflag_f32_e32 v4, v4
	v_add_u32_e32 v2, s2, v2
	v_add_u32_e32 v5, 1, v2
	v_readlane_b32 s2, v244, 24
	v_mul_f32_e32 v3, 0x4f7ffffe, v4
	v_cvt_u32_f32_e32 v3, v3
	v_sub_u32_e32 v4, 0, v1
	v_readlane_b32 s3, v244, 25
	s_add_u32 s6, s2, 0x7500
	v_mul_lo_u32 v4, v4, v3
	v_mul_hi_u32 v4, v3, v4
	v_add_u32_e32 v3, v3, v4
	v_mul_hi_u32 v3, v2, v3
	v_mul_lo_u32 v4, v3, v1
	v_sub_u32_e32 v2, v2, v4
	v_add_u32_e32 v6, 1, v3
	v_cmp_ge_u32_e32 vcc, v2, v1
	v_sub_u32_e32 v4, v2, v1
	s_addc_u32 s7, s3, 0
	v_cndmask_b32_e32 v3, v3, v6, vcc
	v_cndmask_b32_e32 v2, v2, v4, vcc
	v_add_u32_e32 v4, 1, v3
	v_cmp_ge_u32_e32 vcc, v2, v1
	s_nop 1
	v_cndmask_b32_e32 v4, v3, v4, vcc
	v_mul_lo_u32 v2, v1, v4
	v_add_u32_e32 v1, v2, v1
	v_mov_b32_e32 v253, v1
	v_cmp_ne_u32_e32 vcc, v5, v1
	v_mov_b64_e32 v[2:3], s[6:7]
	s_and_saveexec_b64 s[2:3], vcc
	s_cbranch_execz .LBB0_1000
	v_mov_b32_e32 v1, 0
	global_load_dword v2, v1, s[6:7] offset:-256 sc1
	s_mov_b64 s[12:13], 0
	s_waitcnt vmcnt(0)
	v_cmp_lt_u32_e32 vcc, v2, v253
	s_and_saveexec_b64 s[10:11], vcc
	s_cbranch_execz .LBB0_999
	v_readlane_b32 s8, v244, 24
	v_readlane_b32 s9, v244, 25
	s_add_u32 s8, s8, 0x4200
	s_addc_u32 s9, s9, 0
	s_mov_b32 s22, 1
	s_branch .LBB0_992

; __device__ __forceinline__ unsigned xb_ld(unsigned* p)              { return __hip_atomic_load(p, __ATOMIC_RELAXED, __HIP_MEMORY_SCOPE_AGENT); }
; #define XB_SPIN(cond, bar) do { unsigned _sp = 0; while (cond) { __builtin_amdgcn_s_sleep(1); \
;     if ((++_sp & 255u) == 0u) { if (xb_ld(&(bar)[XB_TMO])) break; if (_sp > XB_SPIN_CAP) { atomicAdd(&(bar)[XB_TMO], 1u); break; } } } } while (0)
; __device__ __forceinline__ void xcd_barrier(const XcdBarrier& b) {
;     ...
;             else XB_SPIN(xb_ld(&bar[XB_TOPGEN]) == tg, bar);
.LBB0_996:
	global_load_dword v2, v1, s[6:7] offset:-256 sc1
	s_add_i32 s22, s22, 1
	s_mov_b64 s[16:17], -1
	s_waitcnt vmcnt(0)
	v_cmp_ge_u32_e32 vcc, v2, v253
	s_orn2_b64 s[20:21], vcc, exec
	s_branch .LBB0_991

; __device__ __forceinline__ unsigned xb_ld(unsigned* p)              { return __hip_atomic_load(p, __ATOMIC_RELAXED, __HIP_MEMORY_SCOPE_AGENT); }
; __device__ __forceinline__ unsigned xb_add(unsigned* p, unsigned v) { return __hip_atomic_fetch_add(p, v, __ATOMIC_RELAXED, __HIP_MEMORY_SCOPE_AGENT); }
; #define XB_SPIN(cond, bar) do { unsigned _sp = 0; while (cond) { __builtin_amdgcn_s_sleep(1); \
;     if ((++_sp & 255u) == 0u) { if (xb_ld(&(bar)[XB_TMO])) break; if (_sp > XB_SPIN_CAP) { atomicAdd(&(bar)[XB_TMO], 1u); break; } } } } while (0)
; __device__ __forceinline__ void xcd_barrier(const XcdBarrier& b) {
;     ...
;         const unsigned old = xb_add(&bar[XB_XSUB(b.x)], 1u);
;         const unsigned gen = old / nloc;
;         if (old + 1u == (gen + 1u) * nloc) {
;             __builtin_amdgcn_fence(__ATOMIC_RELEASE, "agent");
;             asm volatile("s_waitcnt vmcnt(0)" ::: "memory");
;             const unsigned og = xb_add(&bar[XB_TOP], 1u);
;             const unsigned tg = og / nx;
;             if (og + 1u == (tg + 1u) * nx) xb_add(&bar[XB_TOPGEN], 1u);
;             else XB_SPIN(xb_ld(&bar[XB_TOPGEN]) == tg, bar);
;             __builtin_amdgcn_fence(__ATOMIC_ACQUIRE, "agent");
;             xb_add(&bar[XB_XGEN(b.x)], 1u);
;             asm volatile("s_waitcnt vmcnt(0)" ::: "memory");
;         } else {
;             XB_SPIN(xb_ld(&bar[XB_XGEN(b.x)]) == gen, bar);
;             __builtin_amdgcn_fence(__ATOMIC_ACQUIRE, "agent");
.LBB0_1095:
	s_or_b64 exec, exec, s[6:7]
	v_cvt_f32_u32_e32 v6, v4
	s_waitcnt vmcnt(0)
	v_readfirstlane_b32 s2, v5
	v_sub_u32_e32 v5, 0, v4
	v_rcp_iflag_f32_e32 v6, v6
	v_add_u32_e32 v7, s2, v3
	v_mul_f32_e32 v6, 0x4f7ffffe, v6
	v_cvt_u32_f32_e32 v6, v6
	v_mul_lo_u32 v3, v5, v6
	v_mul_hi_u32 v3, v6, v3
	v_add_u32_e32 v3, v6, v3
	v_mul_hi_u32 v3, v7, v3
	v_mul_lo_u32 v5, v3, v4
	v_sub_u32_e32 v5, v7, v5
	v_add_u32_e32 v6, 1, v3
	v_cmp_ge_u32_e32 vcc, v5, v4
	s_nop 1
	v_cndmask_b32_e32 v3, v3, v6, vcc
	v_sub_u32_e32 v6, v5, v4
	v_cndmask_b32_e32 v5, v5, v6, vcc
	v_add_u32_e32 v6, 1, v3
	v_cmp_ge_u32_e32 vcc, v5, v4
	v_add_u32_e32 v5, 1, v7
	s_nop 0
	v_cndmask_b32_e32 v3, v3, v6, vcc
	v_mul_lo_u32 v6, v4, v3
	v_add_u32_e32 v4, v6, v4
	v_cmp_ne_u32_e32 vcc, v5, v4
	s_and_saveexec_b64 s[2:3], vcc
	s_xor_b64 s[2:3], exec, s[2:3]
	s_cbranch_execz .LBB0_1109
	s_waitcnt lgkmcnt(0)
	v_mov_b32_e32 v255, 0x23f64
	ds_read_b32 v254, v255
	v_mov_b32_e32 v2, 0
	v_readlane_b32 s10, v244, 24
	v_readlane_b32 s11, v244, 25
	s_nop 1
	s_add_u32 s10, s10, 0x7400
	s_addc_u32 s11, s11, 0
	global_load_dword v2, v2, s[10:11] sc1
	s_waitcnt lgkmcnt(0)
	v_mad_u32_u24 v254, v3, v254, v254
	s_waitcnt vmcnt(0)
	v_cmp_lt_u32_e32 vcc, v2, v254
	s_and_saveexec_b64 s[6:7], vcc
	s_cbranch_execz .LBB0_1108
	v_readlane_b32 s8, v244, 24
	v_readlane_b32 s9, v244, 25
	s_add_u32 s8, s8, 0x4200
	s_addc_u32 s9, s9, 0
	s_mov_b32 s22, 1
	s_mov_b64 s[12:13], 0
	v_mov_b32_e32 v2, 0
	s_branch .LBB0_1099

; __device__ __forceinline__ unsigned xb_ld(unsigned* p)              { return __hip_atomic_load(p, __ATOMIC_RELAXED, __HIP_MEMORY_SCOPE_AGENT); }
; #define XB_SPIN(cond, bar) do { unsigned _sp = 0; while (cond) { __builtin_amdgcn_s_sleep(1); \
;     if ((++_sp & 255u) == 0u) { if (xb_ld(&(bar)[XB_TMO])) break; if (_sp > XB_SPIN_CAP) { atomicAdd(&(bar)[XB_TMO], 1u); break; } } } } while (0)
; __device__ __forceinline__ void xcd_barrier(const XcdBarrier& b) {
;     ...
;             XB_SPIN(xb_ld(&bar[XB_XGEN(b.x)]) == gen, bar);
.LBB0_1103:
	global_load_dword v4, v2, s[10:11] sc1
	s_add_i32 s22, s22, 1
	s_mov_b64 s[18:19], -1
	s_waitcnt vmcnt(0)
	v_cmp_ge_u32_e32 vcc, v4, v254
	s_orn2_b64 s[16:17], vcc, exec
	s_branch .LBB0_1098

; __device__ __forceinline__ unsigned xb_ld(unsigned* p)              { return __hip_atomic_load(p, __ATOMIC_RELAXED, __HIP_MEMORY_SCOPE_AGENT); }
; __device__ __forceinline__ unsigned xb_add(unsigned* p, unsigned v) { return __hip_atomic_fetch_add(p, v, __ATOMIC_RELAXED, __HIP_MEMORY_SCOPE_AGENT); }
; #define XB_SPIN(cond, bar) do { unsigned _sp = 0; while (cond) { __builtin_amdgcn_s_sleep(1); \
;     if ((++_sp & 255u) == 0u) { if (xb_ld(&(bar)[XB_TMO])) break; if (_sp > XB_SPIN_CAP) { atomicAdd(&(bar)[XB_TMO], 1u); break; } } } } while (0)
; __device__ __forceinline__ void xcd_barrier(const XcdBarrier& b) {
;     ...
;         if (old + 1u == (gen + 1u) * nloc) {
;             __builtin_amdgcn_fence(__ATOMIC_RELEASE, "agent");
;             asm volatile("s_waitcnt vmcnt(0)" ::: "memory");
;             const unsigned og = xb_add(&bar[XB_TOP], 1u);
;             const unsigned tg = og / nx;
;             if (og + 1u == (tg + 1u) * nx) xb_add(&bar[XB_TOPGEN], 1u);
;             else XB_SPIN(xb_ld(&bar[XB_TOPGEN]) == tg, bar);
.LBB0_1112:
	s_or_b64 exec, exec, s[6:7]
	v_cvt_f32_u32_e32 v5, v2
	s_waitcnt vmcnt(0)
	v_readfirstlane_b32 s2, v4
	s_mov_b64 s[8:9], -1
	v_rcp_iflag_f32_e32 v5, v5
	v_add_u32_e32 v3, s2, v3
	v_add_u32_e32 v6, 1, v3
	v_readlane_b32 s2, v244, 24
	v_mul_f32_e32 v4, 0x4f7ffffe, v5
	v_cvt_u32_f32_e32 v4, v4
	v_sub_u32_e32 v5, 0, v2
	v_readlane_b32 s3, v244, 25
	s_add_u32 s6, s2, 0x7500
	v_mul_lo_u32 v5, v5, v4
	v_mul_hi_u32 v5, v4, v5
	v_add_u32_e32 v4, v4, v5
	v_mul_hi_u32 v4, v3, v4
	v_mul_lo_u32 v5, v4, v2
	v_sub_u32_e32 v3, v3, v5
	v_add_u32_e32 v7, 1, v4
	v_cmp_ge_u32_e32 vcc, v3, v2
	v_sub_u32_e32 v5, v3, v2
	s_addc_u32 s7, s3, 0
	v_cndmask_b32_e32 v4, v4, v7, vcc
	v_cndmask_b32_e32 v3, v3, v5, vcc
	v_add_u32_e32 v5, 1, v4
	v_cmp_ge_u32_e32 vcc, v3, v2
	s_nop 1
	v_cndmask_b32_e32 v4, v4, v5, vcc
	v_mul_lo_u32 v3, v2, v4
	v_add_u32_e32 v2, v3, v2
	v_mov_b32_e32 v253, v2
	v_cmp_ne_u32_e32 vcc, v6, v2
	v_mov_b64_e32 v[2:3], s[6:7]
	s_and_saveexec_b64 s[2:3], vcc
	s_cbranch_execz .LBB0_1124
	v_mov_b32_e32 v2, 0
	global_load_dword v3, v2, s[6:7] offset:-256 sc1
	s_mov_b64 s[12:13], 0
	s_waitcnt vmcnt(0)
	v_cmp_lt_u32_e32 vcc, v3, v253
	s_and_saveexec_b64 s[10:11], vcc
	s_cbranch_execz .LBB0_1123
	v_readlane_b32 s8, v244, 24
	v_readlane_b32 s9, v244, 25
	s_add_u32 s8, s8, 0x4200
	s_addc_u32 s9, s9, 0
	s_mov_b32 s22, 1
	s_branch .LBB0_1116

; __device__ __forceinline__ unsigned xb_ld(unsigned* p)              { return __hip_atomic_load(p, __ATOMIC_RELAXED, __HIP_MEMORY_SCOPE_AGENT); }
; #define XB_SPIN(cond, bar) do { unsigned _sp = 0; while (cond) { __builtin_amdgcn_s_sleep(1); \
;     if ((++_sp & 255u) == 0u) { if (xb_ld(&(bar)[XB_TMO])) break; if (_sp > XB_SPIN_CAP) { atomicAdd(&(bar)[XB_TMO], 1u); break; } } } } while (0)
; __device__ __forceinline__ void xcd_barrier(const XcdBarrier& b) {
;     ...
;             else XB_SPIN(xb_ld(&bar[XB_TOPGEN]) == tg, bar);
.LBB0_1120:
	global_load_dword v3, v2, s[6:7] offset:-256 sc1
	s_add_i32 s22, s22, 1
	s_mov_b64 s[16:17], -1
	s_waitcnt vmcnt(0)
	v_cmp_ge_u32_e32 vcc, v3, v253
	s_orn2_b64 s[20:21], vcc, exec
	s_branch .LBB0_1115

; __device__ __forceinline__ unsigned xb_add(unsigned* p, unsigned v) { return __hip_atomic_fetch_add(p, v, __ATOMIC_RELAXED, __HIP_MEMORY_SCOPE_AGENT); }
; __device__ __forceinline__ void xcd_barrier(const XcdBarrier& b) {
;     ...
;             __builtin_amdgcn_fence(__ATOMIC_ACQUIRE, "agent");
;             xb_add(&bar[XB_XGEN(b.x)], 1u);
;             asm volatile("s_waitcnt vmcnt(0)" ::: "memory");
.LBB0_1126:
	s_or_b64 exec, exec, s[2:3]
	s_mov_b64 s[2:3], exec
	v_mbcnt_lo_u32_b32 v2, s2, 0
	v_mbcnt_hi_u32_b32 v2, s3, v2
	v_cmp_eq_u32_e32 vcc, 0, v2
	s_waitcnt vmcnt(0)
	buffer_inv sc1
	s_and_saveexec_b64 s[6:7], vcc
	s_cbranch_execz .LBB0_1128
	s_bcnt1_i32_b64 s2, s[2:3]
	v_mov_b32_e32 v2, 0x2000
	v_mov_b32_e32 v3, s2
	s_nop 0

; __device__ __forceinline__ unsigned xb_ld(unsigned* p)              { return __hip_atomic_load(p, __ATOMIC_RELAXED, __HIP_MEMORY_SCOPE_AGENT); }
; __device__ __forceinline__ unsigned xb_add(unsigned* p, unsigned v) { return __hip_atomic_fetch_add(p, v, __ATOMIC_RELAXED, __HIP_MEMORY_SCOPE_AGENT); }
; #define XB_SPIN(cond, bar) do { unsigned _sp = 0; while (cond) { __builtin_amdgcn_s_sleep(1); \
;     if ((++_sp & 255u) == 0u) { if (xb_ld(&(bar)[XB_TMO])) break; if (_sp > XB_SPIN_CAP) { atomicAdd(&(bar)[XB_TMO], 1u); break; } } } } while (0)
; __device__ __forceinline__ void xcd_barrier(const XcdBarrier& b) {
;     ...
;         const unsigned old = xb_add(&bar[XB_XSUB(b.x)], 1u);
;         const unsigned gen = old / nloc;
;         if (old + 1u == (gen + 1u) * nloc) {
;             __builtin_amdgcn_fence(__ATOMIC_RELEASE, "agent");
;             asm volatile("s_waitcnt vmcnt(0)" ::: "memory");
;             const unsigned og = xb_add(&bar[XB_TOP], 1u);
;             const unsigned tg = og / nx;
;             if (og + 1u == (tg + 1u) * nx) xb_add(&bar[XB_TOPGEN], 1u);
;             else XB_SPIN(xb_ld(&bar[XB_TOPGEN]) == tg, bar);
;             __builtin_amdgcn_fence(__ATOMIC_ACQUIRE, "agent");
;             xb_add(&bar[XB_XGEN(b.x)], 1u);
;             asm volatile("s_waitcnt vmcnt(0)" ::: "memory");
;         } else {
;             XB_SPIN(xb_ld(&bar[XB_XGEN(b.x)]) == gen, bar);
;             __builtin_amdgcn_fence(__ATOMIC_ACQUIRE, "agent");
.LBB0_1437:
	s_or_b64 exec, exec, s[6:7]
	v_cvt_f32_u32_e32 v6, v4
	s_waitcnt vmcnt(0)
	v_readfirstlane_b32 s2, v5
	v_sub_u32_e32 v5, 0, v4
	v_rcp_iflag_f32_e32 v6, v6
	v_add_u32_e32 v7, s2, v3
	v_mul_f32_e32 v6, 0x4f7ffffe, v6
	v_cvt_u32_f32_e32 v6, v6
	v_mul_lo_u32 v3, v5, v6
	v_mul_hi_u32 v3, v6, v3
	v_add_u32_e32 v3, v6, v3
	v_mul_hi_u32 v3, v7, v3
	v_mul_lo_u32 v5, v3, v4
	v_sub_u32_e32 v5, v7, v5
	v_add_u32_e32 v6, 1, v3
	v_cmp_ge_u32_e32 vcc, v5, v4
	s_nop 1
	v_cndmask_b32_e32 v3, v3, v6, vcc
	v_sub_u32_e32 v6, v5, v4
	v_cndmask_b32_e32 v5, v5, v6, vcc
	v_add_u32_e32 v6, 1, v3
	v_cmp_ge_u32_e32 vcc, v5, v4
	v_add_u32_e32 v5, 1, v7
	s_nop 0
	v_cndmask_b32_e32 v3, v3, v6, vcc
	v_mul_lo_u32 v6, v4, v3
	v_add_u32_e32 v4, v6, v4
	v_cmp_ne_u32_e32 vcc, v5, v4
	s_and_saveexec_b64 s[2:3], vcc
	s_xor_b64 s[2:3], exec, s[2:3]
	s_cbranch_execz .LBB0_1453
	s_waitcnt lgkmcnt(0)
	v_mov_b32_e32 v255, 0x23f64
	ds_read_b32 v254, v255
	v_mov_b32_e32 v2, 0
	s_add_u32 s10, s54, 0x7400
	s_addc_u32 s11, s55, 0
	global_load_dword v2, v2, s[10:11] sc1
	s_waitcnt lgkmcnt(0)
	v_mad_u32_u24 v254, v3, v254, v254
	s_waitcnt vmcnt(0)
	v_cmp_lt_u32_e32 vcc, v2, v254
	s_and_saveexec_b64 s[6:7], vcc
	s_cbranch_execz .LBB0_1452
	s_add_u32 s8, s54, 0x4200
	s_addc_u32 s9, s55, 0
	s_mov_b32 s22, 1
	s_mov_b64 s[12:13], 0
	v_mov_b32_e32 v2, 0
	s_branch .LBB0_1441

; __device__ __forceinline__ unsigned xb_ld(unsigned* p)              { return __hip_atomic_load(p, __ATOMIC_RELAXED, __HIP_MEMORY_SCOPE_AGENT); }
; __device__ __forceinline__ unsigned xb_add(unsigned* p, unsigned v) { return __hip_atomic_fetch_add(p, v, __ATOMIC_RELAXED, __HIP_MEMORY_SCOPE_AGENT); }
; #define XB_SPIN(cond, bar) do { unsigned _sp = 0; while (cond) { __builtin_amdgcn_s_sleep(1); \
;     if ((++_sp & 255u) == 0u) { if (xb_ld(&(bar)[XB_TMO])) break; if (_sp > XB_SPIN_CAP) { atomicAdd(&(bar)[XB_TMO], 1u); break; } } } } while (0)
; __device__ __forceinline__ void xcd_barrier(const XcdBarrier& b) {
;     ...
;         if (old + 1u == (gen + 1u) * nloc) {
;             __builtin_amdgcn_fence(__ATOMIC_RELEASE, "agent");
;             asm volatile("s_waitcnt vmcnt(0)" ::: "memory");
;             const unsigned og = xb_add(&bar[XB_TOP], 1u);
;             const unsigned tg = og / nx;
;             if (og + 1u == (tg + 1u) * nx) xb_add(&bar[XB_TOPGEN], 1u);
;             else XB_SPIN(xb_ld(&bar[XB_TOPGEN]) == tg, bar);
.LBB0_1456:
	s_or_b64 exec, exec, s[6:7]
	v_cvt_f32_u32_e32 v5, v2
	s_waitcnt vmcnt(0)
	v_readfirstlane_b32 s2, v4
	s_add_u32 s6, s54, 0x7500
	s_addc_u32 s7, s55, 0
	v_rcp_iflag_f32_e32 v5, v5
	v_add_u32_e32 v3, s2, v3
	v_add_u32_e32 v6, 1, v3
	s_mov_b64 s[8:9], -1
	v_mul_f32_e32 v4, 0x4f7ffffe, v5
	v_cvt_u32_f32_e32 v4, v4
	v_sub_u32_e32 v5, 0, v2
	v_mul_lo_u32 v5, v5, v4
	v_mul_hi_u32 v5, v4, v5
	v_add_u32_e32 v4, v4, v5
	v_mul_hi_u32 v4, v3, v4
	v_mul_lo_u32 v5, v4, v2
	v_sub_u32_e32 v3, v3, v5
	v_add_u32_e32 v7, 1, v4
	v_cmp_ge_u32_e32 vcc, v3, v2
	v_sub_u32_e32 v5, v3, v2
	s_nop 0
	v_cndmask_b32_e32 v4, v4, v7, vcc
	v_cndmask_b32_e32 v3, v3, v5, vcc
	v_add_u32_e32 v5, 1, v4
	v_cmp_ge_u32_e32 vcc, v3, v2
	s_nop 1
	v_cndmask_b32_e32 v4, v4, v5, vcc
	v_mul_lo_u32 v3, v2, v4
	v_add_u32_e32 v2, v3, v2
	v_mov_b32_e32 v253, v2
	v_cmp_ne_u32_e32 vcc, v6, v2
	v_mov_b64_e32 v[2:3], s[6:7]
	s_and_saveexec_b64 s[2:3], vcc
	s_cbranch_execz .LBB0_1468
	v_mov_b32_e32 v2, 0
	global_load_dword v3, v2, s[6:7] offset:-256 sc1
	s_mov_b64 s[12:13], 0
	s_waitcnt vmcnt(0)
	v_cmp_lt_u32_e32 vcc, v3, v253
	s_and_saveexec_b64 s[10:11], vcc
	s_cbranch_execz .LBB0_1467
	s_add_u32 s8, s54, 0x4200
	s_addc_u32 s9, s55, 0
	s_mov_b32 s22, 1
	s_branch .LBB0_1460

; __device__ __forceinline__ unsigned xb_ld(unsigned* p)              { return __hip_atomic_load(p, __ATOMIC_RELAXED, __HIP_MEMORY_SCOPE_AGENT); }
; __device__ __forceinline__ unsigned xb_add(unsigned* p, unsigned v) { return __hip_atomic_fetch_add(p, v, __ATOMIC_RELAXED, __HIP_MEMORY_SCOPE_AGENT); }
; #define XB_SPIN(cond, bar) do { unsigned _sp = 0; while (cond) { __builtin_amdgcn_s_sleep(1); \
;     if ((++_sp & 255u) == 0u) { if (xb_ld(&(bar)[XB_TMO])) break; if (_sp > XB_SPIN_CAP) { atomicAdd(&(bar)[XB_TMO], 1u); break; } } } } while (0)
; __device__ __forceinline__ void xcd_barrier(const XcdBarrier& b) {
;     ...
;         const unsigned old = xb_add(&bar[XB_XSUB(b.x)], 1u);
;         const unsigned gen = old / nloc;
;         if (old + 1u == (gen + 1u) * nloc) {
;             __builtin_amdgcn_fence(__ATOMIC_RELEASE, "agent");
;             asm volatile("s_waitcnt vmcnt(0)" ::: "memory");
;             const unsigned og = xb_add(&bar[XB_TOP], 1u);
;             const unsigned tg = og / nx;
;             if (og + 1u == (tg + 1u) * nx) xb_add(&bar[XB_TOPGEN], 1u);
;             else XB_SPIN(xb_ld(&bar[XB_TOPGEN]) == tg, bar);
;             __builtin_amdgcn_fence(__ATOMIC_ACQUIRE, "agent");
;             xb_add(&bar[XB_XGEN(b.x)], 1u);
;             asm volatile("s_waitcnt vmcnt(0)" ::: "memory");
;         } else {
;             XB_SPIN(xb_ld(&bar[XB_XGEN(b.x)]) == gen, bar);
;             __builtin_amdgcn_fence(__ATOMIC_ACQUIRE, "agent");
.LBB0_1577:
	s_or_b64 exec, exec, s[12:13]
	v_cvt_f32_u32_e32 v6, v4
	s_waitcnt vmcnt(0)
	v_readfirstlane_b32 s2, v5
	v_sub_u32_e32 v5, 0, v4
	v_rcp_iflag_f32_e32 v6, v6
	v_add_u32_e32 v7, s2, v3
	v_mul_f32_e32 v6, 0x4f7ffffe, v6
	v_cvt_u32_f32_e32 v6, v6
	v_mul_lo_u32 v3, v5, v6
	v_mul_hi_u32 v3, v6, v3
	v_add_u32_e32 v3, v6, v3
	v_mul_hi_u32 v3, v7, v3
	v_mul_lo_u32 v5, v3, v4
	v_sub_u32_e32 v5, v7, v5
	v_add_u32_e32 v6, 1, v3
	v_cmp_ge_u32_e32 vcc, v5, v4
	s_nop 1
	v_cndmask_b32_e32 v3, v3, v6, vcc
	v_sub_u32_e32 v6, v5, v4
	v_cndmask_b32_e32 v5, v5, v6, vcc
	v_add_u32_e32 v6, 1, v3
	v_cmp_ge_u32_e32 vcc, v5, v4
	v_add_u32_e32 v5, 1, v7
	s_nop 0
	v_cndmask_b32_e32 v3, v3, v6, vcc
	v_mul_lo_u32 v6, v4, v3
	v_add_u32_e32 v4, v6, v4
	v_cmp_ne_u32_e32 vcc, v5, v4
	s_and_saveexec_b64 s[2:3], vcc
	s_xor_b64 s[2:3], exec, s[2:3]
	s_cbranch_execz .LBB0_1591
	s_waitcnt lgkmcnt(0)
	v_mov_b32_e32 v255, 0x23f64
	ds_read_b32 v254, v255
	v_mov_b32_e32 v2, 0
	s_add_u32 s16, s54, 0x7400
	s_addc_u32 s17, s55, 0
	global_load_dword v2, v2, s[16:17] sc1
	s_waitcnt lgkmcnt(0)
	v_mad_u32_u24 v254, v3, v254, v254
	s_waitcnt vmcnt(0)
	v_cmp_lt_u32_e32 vcc, v2, v254
	s_and_saveexec_b64 s[12:13], vcc
	s_cbranch_execz .LBB0_1590
	s_add_u32 s14, s54, 0x4200
	s_addc_u32 s15, s55, 0
	s_mov_b32 s28, 1
	s_mov_b64 s[18:19], 0
	v_mov_b32_e32 v2, 0
	s_branch .LBB0_1581

; __device__ __forceinline__ unsigned xb_ld(unsigned* p)              { return __hip_atomic_load(p, __ATOMIC_RELAXED, __HIP_MEMORY_SCOPE_AGENT); }
; #define XB_SPIN(cond, bar) do { unsigned _sp = 0; while (cond) { __builtin_amdgcn_s_sleep(1); \
;     if ((++_sp & 255u) == 0u) { if (xb_ld(&(bar)[XB_TMO])) break; if (_sp > XB_SPIN_CAP) { atomicAdd(&(bar)[XB_TMO], 1u); break; } } } } while (0)
; __device__ __forceinline__ void xcd_barrier(const XcdBarrier& b) {
;     ...
;             XB_SPIN(xb_ld(&bar[XB_XGEN(b.x)]) == gen, bar);
.LBB0_1585:
	global_load_dword v4, v2, s[16:17] sc1
	s_add_i32 s28, s28, 1
	s_mov_b64 s[24:25], -1
	s_waitcnt vmcnt(0)
	v_cmp_ge_u32_e32 vcc, v4, v254
	s_orn2_b64 s[22:23], vcc, exec
	s_branch .LBB0_1580

; __device__ __forceinline__ unsigned xb_ld(unsigned* p)              { return __hip_atomic_load(p, __ATOMIC_RELAXED, __HIP_MEMORY_SCOPE_AGENT); }
; __device__ __forceinline__ unsigned xb_add(unsigned* p, unsigned v) { return __hip_atomic_fetch_add(p, v, __ATOMIC_RELAXED, __HIP_MEMORY_SCOPE_AGENT); }
; #define XB_SPIN(cond, bar) do { unsigned _sp = 0; while (cond) { __builtin_amdgcn_s_sleep(1); \
;     if ((++_sp & 255u) == 0u) { if (xb_ld(&(bar)[XB_TMO])) break; if (_sp > XB_SPIN_CAP) { atomicAdd(&(bar)[XB_TMO], 1u); break; } } } } while (0)
; __device__ __forceinline__ void xcd_barrier(const XcdBarrier& b) {
;     ...
;         if (old + 1u == (gen + 1u) * nloc) {
;             __builtin_amdgcn_fence(__ATOMIC_RELEASE, "agent");
;             asm volatile("s_waitcnt vmcnt(0)" ::: "memory");
;             const unsigned og = xb_add(&bar[XB_TOP], 1u);
;             const unsigned tg = og / nx;
;             if (og + 1u == (tg + 1u) * nx) xb_add(&bar[XB_TOPGEN], 1u);
;             else XB_SPIN(xb_ld(&bar[XB_TOPGEN]) == tg, bar);
.LBB0_1594:
	s_or_b64 exec, exec, s[12:13]
	v_cvt_f32_u32_e32 v5, v2
	s_waitcnt vmcnt(0)
	v_readfirstlane_b32 s2, v4
	s_add_u32 s12, s54, 0x7500
	s_addc_u32 s13, s55, 0
	v_rcp_iflag_f32_e32 v5, v5
	v_add_u32_e32 v3, s2, v3
	v_add_u32_e32 v6, 1, v3
	s_mov_b64 s[14:15], -1
	v_mul_f32_e32 v4, 0x4f7ffffe, v5
	v_cvt_u32_f32_e32 v4, v4
	v_sub_u32_e32 v5, 0, v2
	v_mul_lo_u32 v5, v5, v4
	v_mul_hi_u32 v5, v4, v5
	v_add_u32_e32 v4, v4, v5
	v_mul_hi_u32 v4, v3, v4
	v_mul_lo_u32 v5, v4, v2
	v_sub_u32_e32 v3, v3, v5
	v_add_u32_e32 v7, 1, v4
	v_cmp_ge_u32_e32 vcc, v3, v2
	v_sub_u32_e32 v5, v3, v2
	s_nop 0
	v_cndmask_b32_e32 v4, v4, v7, vcc
	v_cndmask_b32_e32 v3, v3, v5, vcc
	v_add_u32_e32 v5, 1, v4
	v_cmp_ge_u32_e32 vcc, v3, v2
	s_nop 1
	v_cndmask_b32_e32 v4, v4, v5, vcc
	v_mul_lo_u32 v3, v2, v4
	v_add_u32_e32 v2, v3, v2
	v_mov_b32_e32 v253, v2
	v_cmp_ne_u32_e32 vcc, v6, v2
	v_mov_b64_e32 v[2:3], s[12:13]
	s_and_saveexec_b64 s[2:3], vcc
	s_cbranch_execz .LBB0_1606
	v_mov_b32_e32 v2, 0
	global_load_dword v3, v2, s[12:13] offset:-256 sc1
	s_mov_b64 s[18:19], 0
	s_waitcnt vmcnt(0)
	v_cmp_lt_u32_e32 vcc, v3, v253
	s_and_saveexec_b64 s[16:17], vcc
	s_cbranch_execz .LBB0_1605
	s_add_u32 s14, s54, 0x4200
	s_addc_u32 s15, s55, 0
	s_mov_b32 s28, 1
	s_branch .LBB0_1598

; __device__ __forceinline__ unsigned xb_ld(unsigned* p)              { return __hip_atomic_load(p, __ATOMIC_RELAXED, __HIP_MEMORY_SCOPE_AGENT); }
; __device__ __forceinline__ unsigned xb_add(unsigned* p, unsigned v) { return __hip_atomic_fetch_add(p, v, __ATOMIC_RELAXED, __HIP_MEMORY_SCOPE_AGENT); }
; #define XB_SPIN(cond, bar) do { unsigned _sp = 0; while (cond) { __builtin_amdgcn_s_sleep(1); \
;     if ((++_sp & 255u) == 0u) { if (xb_ld(&(bar)[XB_TMO])) break; if (_sp > XB_SPIN_CAP) { atomicAdd(&(bar)[XB_TMO], 1u); break; } } } } while (0)
; __device__ __forceinline__ void xcd_barrier(const XcdBarrier& b) {
;     ...
;             const unsigned og = xb_add(&bar[XB_TOP], 1u);
;             const unsigned tg = og / nx;
;             if (og + 1u == (tg + 1u) * nx) xb_add(&bar[XB_TOPGEN], 1u);
;             else XB_SPIN(xb_ld(&bar[XB_TOPGEN]) == tg, bar);
;             __builtin_amdgcn_fence(__ATOMIC_ACQUIRE, "agent");
;             xb_add(&bar[XB_XGEN(b.x)], 1u);
;             asm volatile("s_waitcnt vmcnt(0)" ::: "memory");
;         } else {
;             XB_SPIN(xb_ld(&bar[XB_XGEN(b.x)]) == gen, bar);
.LBB0_1602:
	global_load_dword v3, v2, s[12:13] offset:-256 sc1
	s_add_i32 s28, s28, 1
	s_mov_b64 s[22:23], -1
	s_waitcnt vmcnt(0)
	v_cmp_ge_u32_e32 vcc, v3, v253
	s_orn2_b64 s[26:27], vcc, exec
	s_branch .LBB0_1597

; __device__ __forceinline__ unsigned xb_ld(unsigned* p)              { return __hip_atomic_load(p, __ATOMIC_RELAXED, __HIP_MEMORY_SCOPE_AGENT); }
; __device__ __forceinline__ unsigned xb_add(unsigned* p, unsigned v) { return __hip_atomic_fetch_add(p, v, __ATOMIC_RELAXED, __HIP_MEMORY_SCOPE_AGENT); }
; #define XB_SPIN(cond, bar) do { unsigned _sp = 0; while (cond) { __builtin_amdgcn_s_sleep(1); \
;     if ((++_sp & 255u) == 0u) { if (xb_ld(&(bar)[XB_TMO])) break; if (_sp > XB_SPIN_CAP) { atomicAdd(&(bar)[XB_TMO], 1u); break; } } } } while (0)
; __device__ __forceinline__ void xcd_barrier(const XcdBarrier& b) {
;     ...
;         if (old + 1u == (gen + 1u) * nloc) {
;             __builtin_amdgcn_fence(__ATOMIC_RELEASE, "agent");
;             asm volatile("s_waitcnt vmcnt(0)" ::: "memory");
;             const unsigned og = xb_add(&bar[XB_TOP], 1u);
;             const unsigned tg = og / nx;
;             if (og + 1u == (tg + 1u) * nx) xb_add(&bar[XB_TOPGEN], 1u);
;             else XB_SPIN(xb_ld(&bar[XB_TOPGEN]) == tg, bar);
;             __builtin_amdgcn_fence(__ATOMIC_ACQUIRE, "agent");
;             xb_add(&bar[XB_XGEN(b.x)], 1u);
;             asm volatile("s_waitcnt vmcnt(0)" ::: "memory");
.LBB0_1608:
	s_or_b64 exec, exec, s[2:3]
	s_mov_b64 s[2:3], exec
	v_mbcnt_lo_u32_b32 v2, s2, 0
	v_mbcnt_hi_u32_b32 v2, s3, v2
	v_cmp_eq_u32_e32 vcc, 0, v2
	s_waitcnt vmcnt(0)
	buffer_inv sc1
	s_and_saveexec_b64 s[12:13], vcc
	s_cbranch_execz .LBB0_1610
	s_bcnt1_i32_b64 s2, s[2:3]
	v_mov_b32_e32 v2, 0x2000
	v_mov_b32_e32 v3, s2
	s_nop 0
